# GEMM1 mode-2: reduction words moved to staging buffer SA(1,1), so main-round tiles end without a workgroup barrier
# speedup vs baseline: 1.0109x; 1.0071x over previous
.LBB0_112:
	s_or_b64 exec, exec, s[4:5]
	s_waitcnt lgkmcnt(0)
	s_barrier
	s_load_dword s33, s[0:1], 0xf0
	s_add_u32 s58, s0, 0xa8
	s_addc_u32 s59, s1, 0
	s_add_u32 s4, s0, 0xf0
	s_addc_u32 s5, s1, 0
	s_waitcnt lgkmcnt(0)
	s_abs_i32 s3, s33
	v_cvt_f32_u32_e32 v1, s3
	s_mov_b32 s6, 0
	v_writelane_b32 v255, s4, 0
	v_bfe_u32 v236, v0, 2, 4
	v_rcp_iflag_f32_e32 v1, v1
	v_writelane_b32 v255, s5, 1
	v_writelane_b32 v255, s33, 2
	v_writelane_b32 v255, s6, 3
	v_mul_f32_e32 v1, 0x4f7ffffe, v1
	v_cvt_u32_f32_e32 v1, v1
	s_sub_i32 s6, 0, s3
	s_add_i32 s4, s33, 0x2ff
	s_xor_b32 s5, s4, s33
	v_readfirstlane_b32 s7, v1
	s_mul_i32 s6, s6, s7
	s_mul_hi_u32 s6, s7, s6
	s_abs_i32 s4, s4
	s_add_i32 s7, s7, s6
	s_mul_hi_u32 s6, s4, s7
	s_mul_i32 s7, s6, s3
	s_sub_i32 s4, s4, s7
	s_ashr_i32 s5, s5, 31
	s_add_i32 s7, s6, 1
	s_sub_i32 s8, s4, s3
	s_cmp_ge_u32 s4, s3
	s_cselect_b32 s6, s7, s6
	s_cselect_b32 s4, s8, s4
	s_add_i32 s7, s6, 1
	s_cmp_ge_u32 s4, s3
	s_cselect_b32 s3, s7, s6
	s_xor_b32 s3, s3, s5
	s_sub_i32 s9, s3, s5
	s_cmp_lt_i32 s9, 0
	v_bfe_u32 v239, v0, 2, 2
	v_lshlrev_b32_e32 v238, 4, v0
	v_and_b32_e32 v241, 32, v0
	v_and_b32_e32 v235, 64, v0
	v_lshrrev_b32_e32 v242, 5, v0
	v_lshrrev_b32_e32 v243, 1, v0
	v_lshrrev_b32_e32 v240, 3, v0
	v_and_b32_e32 v197, 15, v0
	v_lshlrev_b32_e32 v237, 6, v0
	v_lshlrev_b32_e32 v199, 11, v236
	s_cbranch_scc1 .LBB0_311
	s_add_u32 s60, s0, 0x78
	s_addc_u32 s61, s1, 0
	s_add_u32 s62, s0, 0x88
	s_addc_u32 s63, s1, 0
	s_add_u32 s64, s0, 0x98
	s_addc_u32 s65, s1, 0
	s_add_u32 s66, s0, 0xa0
	s_addc_u32 s67, s1, 0
	s_add_u32 s68, s0, 0xb0
	s_addc_u32 s69, s1, 0
	s_add_u32 s6, s46, 0x200
	s_addc_u32 s7, s47, 0
	s_add_u32 s74, s46, 0x1000
	s_addc_u32 s75, s47, 0
	s_add_u32 s76, s46, 0x1100
	s_addc_u32 s77, s47, 0
	s_add_u32 s78, s46, 0x1200
	s_addc_u32 s79, s47, 0
	v_writelane_b32 v255, s44, 4
	s_add_u32 s80, s46, 0x1300
	s_addc_u32 s81, s47, 0
	v_writelane_b32 v255, s45, 5
	v_writelane_b32 v255, s6, 6
	s_cmp_eq_u32 s73, 15
	v_bitop3_b32 v5, v238, v241, 48 bitop3:0x6c
	v_writelane_b32 v255, s7, 7
	s_cselect_b64 s[6:7], -1, 0
	v_writelane_b32 v255, s6, 8
	s_cmp_eq_u32 s73, 14
	v_and_or_b32 v7, v242, 4, v239
	v_writelane_b32 v255, s7, 9
	s_cselect_b64 s[6:7], -1, 0
	v_writelane_b32 v255, s6, 10
	s_cmp_eq_u32 s73, 13
	v_and_b32_e32 v1, 24, v243
	v_writelane_b32 v255, s7, 11
	s_cselect_b64 s[6:7], -1, 0
	v_writelane_b32 v255, s6, 12
	s_cmp_eq_u32 s73, 12
	v_or_b32_e32 v6, v5, v235
	v_writelane_b32 v255, s7, 13
	s_cselect_b64 s[6:7], -1, 0
	v_writelane_b32 v255, s6, 14
	s_cmp_eq_u32 s73, 11
	v_or_b32_e32 v2, v7, v1
	v_writelane_b32 v255, s7, 15
	s_cselect_b64 s[6:7], -1, 0
	v_writelane_b32 v255, s6, 16
	s_cmp_eq_u32 s73, 10
	v_and_or_b32 v4, v240, 48, v236
	v_writelane_b32 v255, s7, 17
	s_cselect_b64 s[6:7], -1, 0
	v_writelane_b32 v255, s6, 18
	s_cmp_eq_u32 s73, 9
	v_and_b32_e32 v8, 32, v240
	v_writelane_b32 v255, s7, 19
	s_cselect_b64 s[6:7], -1, 0
	v_writelane_b32 v255, s6, 20
	s_cmp_eq_u32 s73, 8
	v_lshl_or_b32 v138, v4, 11, v6
	v_writelane_b32 v255, s7, 21
	s_cselect_b64 s[6:7], -1, 0
	v_writelane_b32 v255, s6, 22
	s_cmp_eq_u32 s73, 7
	v_or_b32_e32 v4, v2, v8
	v_writelane_b32 v255, s7, 23
	s_cselect_b64 s[6:7], -1, 0
	v_writelane_b32 v255, s6, 24
	s_cmp_eq_u32 s73, 6
	v_or_b32_e32 v9, 0x2000, v238
	v_writelane_b32 v255, s7, 25
	s_cselect_b64 s[6:7], -1, 0
	v_writelane_b32 v255, s6, 26
	s_cmp_eq_u32 s73, 5
	v_lshl_or_b32 v140, v4, 11, v6
	v_writelane_b32 v255, s7, 27
	s_cselect_b64 s[6:7], -1, 0
	v_writelane_b32 v255, s6, 28
	s_cmp_eq_u32 s73, 4
	v_lshrrev_b32_e32 v4, 7, v9
	s_movk_i32 s3, 0x70
	v_writelane_b32 v255, s7, 29
	s_cselect_b64 s[6:7], -1, 0
	s_waitcnt vmcnt(4)
	v_and_or_b32 v10, v4, s3, v236
	v_writelane_b32 v255, s6, 30
	s_cmp_eq_u32 s73, 3
	v_lshl_or_b32 v142, v10, 11, v6
	v_and_b32_e32 v10, 0x60, v4
	v_writelane_b32 v255, s7, 31
	s_cselect_b64 s[6:7], -1, 0
	v_or_b32_e32 v2, v2, v10
	v_writelane_b32 v255, s6, 32
	s_cmp_eq_u32 s73, 2
	v_lshl_or_b32 v144, v2, 11, v6
	v_lshlrev_b32_e32 v209, 1, v1
	v_and_b32_e32 v2, 0x3c0, v237
	v_and_b32_e32 v4, 32, v234
	v_writelane_b32 v255, s7, 33
	s_cselect_b64 s[6:7], -1, 0
	v_bitop3_b32 v210, v209, v4, v2 bitop3:0x36
	v_lshlrev_b32_e32 v2, 4, v16
	v_writelane_b32 v255, s6, 34
	s_cmp_eq_u32 s73, 1
	v_or_b32_e32 v12, 4, v2
	v_or_b32_e32 v14, 8, v2
	v_or_b32_e32 v17, 12, v2
	v_or_b32_e32 v19, 15, v2
	v_writelane_b32 v255, s7, 35
	s_cselect_b64 s[6:7], -1, 0
	v_lshlrev_b32_e32 v11, 10, v16
	v_lshlrev_b32_e32 v13, 6, v12
	v_lshlrev_b32_e32 v15, 6, v14
	v_lshlrev_b32_e32 v18, 6, v17
	v_lshlrev_b32_e32 v20, 6, v19
	v_lshlrev_b32_e32 v2, 5, v16
	v_lshlrev_b32_e32 v16, 8, v16
	s_movk_i32 s3, 0x100
	v_lshlrev_b32_e32 v12, 4, v12
	v_lshlrev_b32_e32 v14, 4, v14
	v_lshlrev_b32_e32 v17, 4, v17
	v_lshlrev_b32_e32 v19, 4, v19
	v_writelane_b32 v255, s6, 36
	s_cmp_eq_u32 s73, 0
	v_bitop3_b32 v16, v16, s3, v197 bitop3:0x36
	v_bitop3_b32 v12, v12, s3, v197 bitop3:0x36
	v_bitop3_b32 v14, v14, s3, v197 bitop3:0x36
	v_bitop3_b32 v17, v17, s3, v197 bitop3:0x36
	v_bitop3_b32 v19, v19, s3, v197 bitop3:0x36
	v_writelane_b32 v255, s7, 37
	s_cselect_b64 s[6:7], -1, 0
	s_lshl_b32 s3, s73, 8
	v_writelane_b32 v255, s6, 38
	s_add_u32 s3, s46, s3
	v_lshrrev_b32_e32 v21, 7, v0
	v_writelane_b32 v255, s7, 39
	s_addc_u32 s6, s47, 0
	s_add_u32 s10, s3, 0x1400
	s_addc_u32 s11, s6, 0
	v_writelane_b32 v255, s10, 40
	v_and_b32_e32 v3, 48, v238
	v_lshl_add_u32 v212, v12, 2, 16
	v_add_u32_e32 v212, 0xc000, v212
	v_writelane_b32 v255, s11, 41
	s_add_u32 s10, s3, 0x2400
	s_addc_u32 s11, s6, 0
	v_writelane_b32 v255, s10, 42
	s_add_u32 s6, s46, 0x3400
	v_lshlrev_b32_e32 v12, 15, v21
	v_writelane_b32 v255, s11, 43
	s_addc_u32 s7, s47, 0
	v_bitop3_b32 v3, v3, v12, v241 bitop3:0xde
	s_load_dwordx2 s[12:13], s[0:1], 0xc8
	s_load_dwordx4 s[48:51], s[0:1], 0x58
	s_load_dwordx4 s[52:55], s[0:1], 0x38
	v_writelane_b32 v255, s6, 44
	v_or3_b32 v148, v3, v199, v235
	v_lshlrev_b32_e32 v3, 4, v9
	s_mov_b32 s3, 0x38000
	v_writelane_b32 v255, s7, 45
	s_add_u32 s6, s46, 0x3500
	v_and_or_b32 v3, v3, s3, v5
	v_bfe_u32 v4, v0, 4, 2
	s_addc_u32 s7, s47, 0
	v_or3_b32 v150, v3, v199, v235
	v_or3_b32 v3, v8, v1, v7
	v_mov_b32_e32 v147, 0
	v_cmp_eq_u32_e64 s[4:5], 0, v4
	v_and_b32_e32 v2, 32, v2
	v_lshlrev_b32_e32 v4, 3, v4
	v_writelane_b32 v255, s6, 46
	v_lshl_add_u32 v22, v197, 2, 16
	v_add_u32_e32 v22, 0xc000, v22
	v_lshl_or_b32 v152, v3, 11, v6
	v_or3_b32 v3, v10, v1, v7
	s_mov_b32 s71, 0
	v_mov_b32_e32 v141, v147
	v_mov_b32_e32 v145, v147
	v_mov_b32_e32 v139, v147
	v_mov_b32_e32 v143, v147
	v_writelane_b32 v255, s7, 47
	v_lshl_add_u32 v211, v16, 2, 16
	v_lshl_add_u32 v213, v14, 2, 16
	v_lshl_add_u32 v214, v17, 2, 16
	v_lshl_add_u32 v215, v19, 2, 16
	v_add_u32_e32 v211, 0xc000, v211
	v_add_u32_e32 v213, 0xc000, v213
	v_add_u32_e32 v214, 0xc000, v214
	v_add_u32_e32 v215, 0xc000, v215
	v_mov_b32_e32 v149, v147
	v_mov_b32_e32 v151, v147
	v_mov_b32_e32 v153, v147
	v_lshl_or_b32 v154, v3, 11, v6
	v_mov_b32_e32 v155, v147
	s_mov_b64 s[90:91], 0x80
	s_mov_b64 s[92:93], 0x40080
	s_mov_b64 s[94:95], 0x100
	s_mov_b64 s[96:97], 0x40100
	s_mov_b64 s[98:99], 0x180
	s_mov_b64 s[6:7], 0x40180
	v_add_u32_e32 v254, v22, v13
	v_add_u32_e32 v208, v22, v15
	v_add_u32_e32 v198, v22, v18
	v_add_u32_e32 v196, v22, v20
	v_lshlrev_b32_e32 v146, 2, v2
	v_lshlrev_b32_e32 v156, 2, v4
	s_mov_b32 s8, 0x3c800000
	s_mov_b32 s11, 0x800000
	v_mbcnt_hi_u32_b32 v220, -1, v176
	v_add_u32_e32 v221, v22, v11
	s_mov_b32 s83, 0
	s_mov_b32 s10, 0x45800000
	s_branch .LBB0_115

.LBB0_302:
	v_cvt_pk_bf16_f32 v130, v130, v131
	v_cvt_pk_bf16_f32 v131, v132, v133
	v_cvt_pk_bf16_f32 v132, v134, v135
	v_cvt_pk_bf16_f32 v133, v136, v137
	s_and_b64 vcc, exec, s[40:41]
	global_store_dwordx4 v[160:161], v[130:133], off offset:256
	s_cbranch_vccnz .LBB0_304
	s_cmp_lt_i32 s83, s9
	s_cbranch_scc1 .Lg1_nobar
	s_barrier
.Lg1_nobar:
.LBB0_304:
	s_mov_b64 s[24:25], 0
